# scan: one counted lgkm wait per step (K/WR operands fetched two steps ahead in the second half of the step, rest one step ahead)
# baseline (speedup 1.0000x reference)
.LBB0_65:
	s_bitcmp1_b32 s40, 0
	s_cselect_b32 s2, 0x5500, 0
	v_lshl_or_b32 v94, v93, 2, s2
	v_lshl_add_u32 v95, v0, 2, s2
	v_mov_b32_e32 v96, s2
	v_mul_u32_u24_e32 v46, 0x154, v93
	v_add_u32_e32 v47, v46, v96
	v_add_u32_e32 v46, v46, v95
	ds_read_b64 v[44:45], v47 offset:1344
	ds_read_b32 v48, v46 offset:1280
	ds_read_b128 v[110:113], v94
	ds_read_b128 v[126:129], v94 offset:1024
	ds_read_b128 v[122:125], v94 offset:768
	ds_read_b32 v130, v95 offset:1280
	ds_read_b128 v[118:121], v94 offset:512
	ds_read_b128 v[114:117], v94 offset:256
	ds_read_b128 v[134:137], v94 offset:1360
	ds_read_b128 v[150:153], v94 offset:2384
	s_mov_b64 s[2:3], 0x100
	s_mov_b64 s[20:21], 0x800
	s_waitcnt lgkmcnt(6)
	v_pk_mul_f32 v[24:25], v[30:31], v[112:113]
	v_pk_mul_f32 v[26:27], v[30:31], v[128:129]
	v_pk_fma_f32 v[24:25], v[28:29], v[110:111], v[24:25]
	v_pk_fma_f32 v[26:27], v[28:29], v[126:127], v[26:27]
	v_add_f32_e32 v34, v24, v25
	ds_read_b128 v[146:149], v94 offset:2128
	v_add_f32_e32 v50, v26, v27
	v_add_f32_dpp v34, v34, v34 quad_perm:[1,0,3,2] row_mask:0xf bank_mask:0xf bound_ctrl:1
	ds_read_b32 v154, v95 offset:2640
	ds_read_b128 v[142:145], v94 offset:1872
	v_add_f32_dpp v34, v34, v34 quad_perm:[2,3,0,1] row_mask:0xf bank_mask:0xf bound_ctrl:1
	s_waitcnt lgkmcnt(3)
	v_pk_mul_f32 v[36:37], v[122:123], v[130:131] op_sel_hi:[1,0]
	v_pk_mul_f32 v[38:39], v[124:125], v[130:131] op_sel_hi:[1,0]
	v_add_f32_dpp v34, v34, v34 row_ror:4 row_mask:0xf bank_mask:0xf bound_ctrl:1
	v_pk_fma_f32 v[36:37], v[28:29], v[118:119], v[36:37]
	v_pk_fma_f32 v[38:39], v[30:31], v[120:121], v[38:39]
	v_add_f32_dpp v34, v34, v34 row_ror:8 row_mask:0xf bank_mask:0xf bound_ctrl:1
	ds_read_b128 v[110:113], v94 offset:2720
	ds_read_b128 v[126:129], v94 offset:3744
	v_pk_fma_f32 v[28:29], v[114:115], v[34:35], v[36:37] op_sel_hi:[1,0,1] neg_lo:[0,1,0] neg_hi:[0,1,0]
	v_pk_fma_f32 v[30:31], v[116:117], v[34:35], v[38:39] op_sel_hi:[1,0,1] neg_lo:[0,1,0] neg_hi:[0,1,0]
	v_cndmask_b32_e64 v42, 0, v34, s[30:31]
	ds_read_b128 v[138:141], v94 offset:1616
	v_pk_mul_f32 v[24:25], v[30:31], v[136:137]
	v_pk_mul_f32 v[26:27], v[30:31], v[152:153]
	v_pk_fma_f32 v[24:25], v[28:29], v[134:135], v[24:25]
	v_pk_fma_f32 v[26:27], v[28:29], v[150:151], v[26:27]
	v_add_f32_e32 v34, v24, v25
	ds_read_b128 v[122:125], v94 offset:3488
	v_add_f32_e32 v51, v26, v27
	v_add_f32_dpp v34, v34, v34 quad_perm:[1,0,3,2] row_mask:0xf bank_mask:0xf bound_ctrl:1
	ds_read_b32 v130, v95 offset:4000
	ds_read_b128 v[118:121], v94 offset:3232
	v_add_f32_dpp v34, v34, v34 quad_perm:[2,3,0,1] row_mask:0xf bank_mask:0xf bound_ctrl:1
	s_waitcnt lgkmcnt(3)
	v_pk_mul_f32 v[36:37], v[146:147], v[154:155] op_sel_hi:[1,0]
	v_pk_mul_f32 v[38:39], v[148:149], v[154:155] op_sel_hi:[1,0]
	v_add_f32_dpp v34, v34, v34 row_ror:4 row_mask:0xf bank_mask:0xf bound_ctrl:1
	v_pk_fma_f32 v[36:37], v[28:29], v[142:143], v[36:37]
	v_pk_fma_f32 v[38:39], v[30:31], v[144:145], v[38:39]
	v_add_f32_dpp v34, v34, v34 row_ror:8 row_mask:0xf bank_mask:0xf bound_ctrl:1
	ds_read_b128 v[134:137], v94 offset:4080
	ds_read_b128 v[150:153], v94 offset:5104
	v_pk_fma_f32 v[28:29], v[138:139], v[34:35], v[36:37] op_sel_hi:[1,0,1] neg_lo:[0,1,0] neg_hi:[0,1,0]
	v_pk_fma_f32 v[30:31], v[140:141], v[34:35], v[38:39] op_sel_hi:[1,0,1] neg_lo:[0,1,0] neg_hi:[0,1,0]
	v_cndmask_b32_e64 v42, v42, v34, s[70:71]
	ds_read_b128 v[114:117], v94 offset:2976
	v_pk_mul_f32 v[24:25], v[30:31], v[112:113]
	v_pk_mul_f32 v[26:27], v[30:31], v[128:129]
	v_pk_fma_f32 v[24:25], v[28:29], v[110:111], v[24:25]
	v_pk_fma_f32 v[26:27], v[28:29], v[126:127], v[26:27]
	v_add_f32_e32 v34, v24, v25
	ds_read_b128 v[146:149], v94 offset:4848
	v_add_f32_e32 v52, v26, v27
	v_add_f32_dpp v34, v34, v34 quad_perm:[1,0,3,2] row_mask:0xf bank_mask:0xf bound_ctrl:1
	ds_read_b32 v154, v95 offset:5360
	ds_read_b128 v[142:145], v94 offset:4592
	v_add_f32_dpp v34, v34, v34 quad_perm:[2,3,0,1] row_mask:0xf bank_mask:0xf bound_ctrl:1
	s_waitcnt lgkmcnt(3)
	v_pk_mul_f32 v[36:37], v[122:123], v[130:131] op_sel_hi:[1,0]
	v_pk_mul_f32 v[38:39], v[124:125], v[130:131] op_sel_hi:[1,0]
	v_add_f32_dpp v34, v34, v34 row_ror:4 row_mask:0xf bank_mask:0xf bound_ctrl:1
	v_pk_fma_f32 v[36:37], v[28:29], v[118:119], v[36:37]
	v_pk_fma_f32 v[38:39], v[30:31], v[120:121], v[38:39]
	v_add_f32_dpp v34, v34, v34 row_ror:8 row_mask:0xf bank_mask:0xf bound_ctrl:1
	ds_read_b128 v[110:113], v94 offset:5440
	ds_read_b128 v[126:129], v94 offset:6464
	v_pk_fma_f32 v[28:29], v[114:115], v[34:35], v[36:37] op_sel_hi:[1,0,1] neg_lo:[0,1,0] neg_hi:[0,1,0]
	v_pk_fma_f32 v[30:31], v[116:117], v[34:35], v[38:39] op_sel_hi:[1,0,1] neg_lo:[0,1,0] neg_hi:[0,1,0]
	v_cndmask_b32_e64 v42, v42, v34, s[72:73]
	ds_read_b128 v[138:141], v94 offset:4336
	v_pk_mul_f32 v[24:25], v[30:31], v[136:137]
	v_pk_mul_f32 v[26:27], v[30:31], v[152:153]
	v_pk_fma_f32 v[24:25], v[28:29], v[134:135], v[24:25]
	v_pk_fma_f32 v[26:27], v[28:29], v[150:151], v[26:27]
	v_add_f32_e32 v34, v24, v25
	ds_read_b128 v[122:125], v94 offset:6208
	v_add_f32_e32 v53, v26, v27
	v_add_f32_dpp v34, v34, v34 quad_perm:[1,0,3,2] row_mask:0xf bank_mask:0xf bound_ctrl:1
	ds_read_b32 v130, v95 offset:6720
	ds_read_b128 v[118:121], v94 offset:5952
	v_add_f32_dpp v34, v34, v34 quad_perm:[2,3,0,1] row_mask:0xf bank_mask:0xf bound_ctrl:1
	s_waitcnt lgkmcnt(3)
	v_pk_mul_f32 v[36:37], v[146:147], v[154:155] op_sel_hi:[1,0]
	v_pk_mul_f32 v[38:39], v[148:149], v[154:155] op_sel_hi:[1,0]
	v_add_f32_dpp v34, v34, v34 row_ror:4 row_mask:0xf bank_mask:0xf bound_ctrl:1
	v_pk_fma_f32 v[36:37], v[28:29], v[142:143], v[36:37]
	v_pk_fma_f32 v[38:39], v[30:31], v[144:145], v[38:39]
	v_add_f32_dpp v34, v34, v34 row_ror:8 row_mask:0xf bank_mask:0xf bound_ctrl:1
	ds_read_b128 v[134:137], v94 offset:6800
	ds_read_b128 v[150:153], v94 offset:7824
	v_pk_fma_f32 v[28:29], v[138:139], v[34:35], v[36:37] op_sel_hi:[1,0,1] neg_lo:[0,1,0] neg_hi:[0,1,0]
	v_pk_fma_f32 v[30:31], v[140:141], v[34:35], v[38:39] op_sel_hi:[1,0,1] neg_lo:[0,1,0] neg_hi:[0,1,0]
	v_cndmask_b32_e64 v42, v42, v34, s[74:75]
	ds_read_b128 v[114:117], v94 offset:5696
	v_pk_mul_f32 v[24:25], v[30:31], v[112:113]
	v_pk_mul_f32 v[26:27], v[30:31], v[128:129]
	v_pk_fma_f32 v[24:25], v[28:29], v[110:111], v[24:25]
	v_pk_fma_f32 v[26:27], v[28:29], v[126:127], v[26:27]
	v_add_f32_e32 v34, v24, v25
	ds_read_b128 v[146:149], v94 offset:7568
	v_add_f32_e32 v54, v26, v27
	v_add_f32_dpp v34, v34, v34 quad_perm:[1,0,3,2] row_mask:0xf bank_mask:0xf bound_ctrl:1
	ds_read_b32 v154, v95 offset:8080
	ds_read_b128 v[142:145], v94 offset:7312
	v_add_f32_dpp v34, v34, v34 quad_perm:[2,3,0,1] row_mask:0xf bank_mask:0xf bound_ctrl:1
	s_waitcnt lgkmcnt(3)
	v_pk_mul_f32 v[36:37], v[122:123], v[130:131] op_sel_hi:[1,0]
	v_pk_mul_f32 v[38:39], v[124:125], v[130:131] op_sel_hi:[1,0]
	v_add_f32_dpp v34, v34, v34 row_ror:4 row_mask:0xf bank_mask:0xf bound_ctrl:1
	v_pk_fma_f32 v[36:37], v[28:29], v[118:119], v[36:37]
	v_pk_fma_f32 v[38:39], v[30:31], v[120:121], v[38:39]
	v_add_f32_dpp v34, v34, v34 row_ror:8 row_mask:0xf bank_mask:0xf bound_ctrl:1
	ds_read_b128 v[110:113], v94 offset:8160
	ds_read_b128 v[126:129], v94 offset:9184
	v_pk_fma_f32 v[28:29], v[114:115], v[34:35], v[36:37] op_sel_hi:[1,0,1] neg_lo:[0,1,0] neg_hi:[0,1,0]
	v_pk_fma_f32 v[30:31], v[116:117], v[34:35], v[38:39] op_sel_hi:[1,0,1] neg_lo:[0,1,0] neg_hi:[0,1,0]
	v_cndmask_b32_e64 v42, v42, v34, s[82:83]
	ds_read_b128 v[138:141], v94 offset:7056
	v_pk_mul_f32 v[24:25], v[30:31], v[136:137]
	v_pk_mul_f32 v[26:27], v[30:31], v[152:153]
	v_pk_fma_f32 v[24:25], v[28:29], v[134:135], v[24:25]
	v_pk_fma_f32 v[26:27], v[28:29], v[150:151], v[26:27]
	v_add_f32_e32 v34, v24, v25
	ds_read_b128 v[122:125], v94 offset:8928
	v_add_f32_e32 v55, v26, v27
	v_add_f32_dpp v34, v34, v34 quad_perm:[1,0,3,2] row_mask:0xf bank_mask:0xf bound_ctrl:1
	ds_read_b32 v130, v95 offset:9440
	ds_read_b128 v[118:121], v94 offset:8672
	v_add_f32_dpp v34, v34, v34 quad_perm:[2,3,0,1] row_mask:0xf bank_mask:0xf bound_ctrl:1
	s_waitcnt lgkmcnt(3)
	v_pk_mul_f32 v[36:37], v[146:147], v[154:155] op_sel_hi:[1,0]
	v_pk_mul_f32 v[38:39], v[148:149], v[154:155] op_sel_hi:[1,0]
	v_add_f32_dpp v34, v34, v34 row_ror:4 row_mask:0xf bank_mask:0xf bound_ctrl:1
	v_pk_fma_f32 v[36:37], v[28:29], v[142:143], v[36:37]
	v_pk_fma_f32 v[38:39], v[30:31], v[144:145], v[38:39]
	v_add_f32_dpp v34, v34, v34 row_ror:8 row_mask:0xf bank_mask:0xf bound_ctrl:1
	ds_read_b128 v[134:137], v94 offset:9520
	ds_read_b128 v[150:153], v94 offset:10544
	v_pk_fma_f32 v[28:29], v[138:139], v[34:35], v[36:37] op_sel_hi:[1,0,1] neg_lo:[0,1,0] neg_hi:[0,1,0]
	v_pk_fma_f32 v[30:31], v[140:141], v[34:35], v[38:39] op_sel_hi:[1,0,1] neg_lo:[0,1,0] neg_hi:[0,1,0]
	v_cndmask_b32_e64 v42, v42, v34, s[48:49]
	ds_read_b128 v[114:117], v94 offset:8416
	v_pk_mul_f32 v[24:25], v[30:31], v[112:113]
	v_pk_mul_f32 v[26:27], v[30:31], v[128:129]
	v_pk_fma_f32 v[24:25], v[28:29], v[110:111], v[24:25]
	v_pk_fma_f32 v[26:27], v[28:29], v[126:127], v[26:27]
	v_add_f32_e32 v34, v24, v25
	ds_read_b128 v[146:149], v94 offset:10288
	v_add_f32_e32 v56, v26, v27
	v_add_f32_dpp v34, v34, v34 quad_perm:[1,0,3,2] row_mask:0xf bank_mask:0xf bound_ctrl:1
	ds_read_b32 v154, v95 offset:10800
	ds_read_b128 v[142:145], v94 offset:10032
	v_add_f32_dpp v34, v34, v34 quad_perm:[2,3,0,1] row_mask:0xf bank_mask:0xf bound_ctrl:1
	s_waitcnt lgkmcnt(3)
	v_pk_mul_f32 v[36:37], v[122:123], v[130:131] op_sel_hi:[1,0]
	v_pk_mul_f32 v[38:39], v[124:125], v[130:131] op_sel_hi:[1,0]
	v_add_f32_dpp v34, v34, v34 row_ror:4 row_mask:0xf bank_mask:0xf bound_ctrl:1
	v_pk_fma_f32 v[36:37], v[28:29], v[118:119], v[36:37]
	v_pk_fma_f32 v[38:39], v[30:31], v[120:121], v[38:39]
	v_add_f32_dpp v34, v34, v34 row_ror:8 row_mask:0xf bank_mask:0xf bound_ctrl:1
	ds_read_b128 v[110:113], v94 offset:10880
	ds_read_b128 v[126:129], v94 offset:11904
	v_pk_fma_f32 v[28:29], v[114:115], v[34:35], v[36:37] op_sel_hi:[1,0,1] neg_lo:[0,1,0] neg_hi:[0,1,0]
	v_pk_fma_f32 v[30:31], v[116:117], v[34:35], v[38:39] op_sel_hi:[1,0,1] neg_lo:[0,1,0] neg_hi:[0,1,0]
	v_cndmask_b32_e64 v42, v42, v34, s[38:39]
	ds_read_b128 v[138:141], v94 offset:9776
	v_pk_mul_f32 v[24:25], v[30:31], v[136:137]
	v_pk_mul_f32 v[26:27], v[30:31], v[152:153]
	v_pk_fma_f32 v[24:25], v[28:29], v[134:135], v[24:25]
	v_pk_fma_f32 v[26:27], v[28:29], v[150:151], v[26:27]
	v_add_f32_e32 v34, v24, v25
	ds_read_b128 v[122:125], v94 offset:11648
	v_add_f32_e32 v57, v26, v27
	v_add_f32_dpp v34, v34, v34 quad_perm:[1,0,3,2] row_mask:0xf bank_mask:0xf bound_ctrl:1
	ds_read_b32 v130, v95 offset:12160
	ds_read_b128 v[118:121], v94 offset:11392
	v_add_f32_dpp v34, v34, v34 quad_perm:[2,3,0,1] row_mask:0xf bank_mask:0xf bound_ctrl:1
	s_waitcnt lgkmcnt(3)
	v_pk_mul_f32 v[36:37], v[146:147], v[154:155] op_sel_hi:[1,0]
	v_pk_mul_f32 v[38:39], v[148:149], v[154:155] op_sel_hi:[1,0]
	v_add_f32_dpp v34, v34, v34 row_ror:4 row_mask:0xf bank_mask:0xf bound_ctrl:1
	v_pk_fma_f32 v[36:37], v[28:29], v[142:143], v[36:37]
	v_pk_fma_f32 v[38:39], v[30:31], v[144:145], v[38:39]
	v_add_f32_dpp v34, v34, v34 row_ror:8 row_mask:0xf bank_mask:0xf bound_ctrl:1
	ds_read_b128 v[134:137], v94 offset:12240
	ds_read_b128 v[150:153], v94 offset:13264
	v_pk_fma_f32 v[28:29], v[138:139], v[34:35], v[36:37] op_sel_hi:[1,0,1] neg_lo:[0,1,0] neg_hi:[0,1,0]
	v_pk_fma_f32 v[30:31], v[140:141], v[34:35], v[38:39] op_sel_hi:[1,0,1] neg_lo:[0,1,0] neg_hi:[0,1,0]
	v_cndmask_b32_e64 v42, v42, v34, s[42:43]
	ds_read_b128 v[114:117], v94 offset:11136
	v_pk_mul_f32 v[24:25], v[30:31], v[112:113]
	v_pk_mul_f32 v[26:27], v[30:31], v[128:129]
	v_pk_fma_f32 v[24:25], v[28:29], v[110:111], v[24:25]
	v_pk_fma_f32 v[26:27], v[28:29], v[126:127], v[26:27]
	v_add_f32_e32 v34, v24, v25
	ds_read_b128 v[146:149], v94 offset:13008
	v_add_f32_e32 v58, v26, v27
	v_add_f32_dpp v34, v34, v34 quad_perm:[1,0,3,2] row_mask:0xf bank_mask:0xf bound_ctrl:1
	ds_read_b32 v154, v95 offset:13520
	ds_read_b128 v[142:145], v94 offset:12752
	v_add_f32_dpp v34, v34, v34 quad_perm:[2,3,0,1] row_mask:0xf bank_mask:0xf bound_ctrl:1
	s_waitcnt lgkmcnt(3)
	v_pk_mul_f32 v[36:37], v[122:123], v[130:131] op_sel_hi:[1,0]
	v_pk_mul_f32 v[38:39], v[124:125], v[130:131] op_sel_hi:[1,0]
	v_add_f32_dpp v34, v34, v34 row_ror:4 row_mask:0xf bank_mask:0xf bound_ctrl:1
	v_pk_fma_f32 v[36:37], v[28:29], v[118:119], v[36:37]
	v_pk_fma_f32 v[38:39], v[30:31], v[120:121], v[38:39]
	v_add_f32_dpp v34, v34, v34 row_ror:8 row_mask:0xf bank_mask:0xf bound_ctrl:1
	ds_read_b128 v[110:113], v94 offset:13600
	ds_read_b128 v[126:129], v94 offset:14624
	v_pk_fma_f32 v[28:29], v[114:115], v[34:35], v[36:37] op_sel_hi:[1,0,1] neg_lo:[0,1,0] neg_hi:[0,1,0]
	v_pk_fma_f32 v[30:31], v[116:117], v[34:35], v[38:39] op_sel_hi:[1,0,1] neg_lo:[0,1,0] neg_hi:[0,1,0]
	v_cndmask_b32_e64 v42, v42, v34, s[44:45]
	ds_read_b128 v[138:141], v94 offset:12496
	v_pk_mul_f32 v[24:25], v[30:31], v[136:137]
	v_pk_mul_f32 v[26:27], v[30:31], v[152:153]
	v_pk_fma_f32 v[24:25], v[28:29], v[134:135], v[24:25]
	v_pk_fma_f32 v[26:27], v[28:29], v[150:151], v[26:27]
	v_add_f32_e32 v34, v24, v25
	ds_read_b128 v[122:125], v94 offset:14368
	v_add_f32_e32 v59, v26, v27
	v_add_f32_dpp v34, v34, v34 quad_perm:[1,0,3,2] row_mask:0xf bank_mask:0xf bound_ctrl:1
	ds_read_b32 v130, v95 offset:14880
	ds_read_b128 v[118:121], v94 offset:14112
	v_add_f32_dpp v34, v34, v34 quad_perm:[2,3,0,1] row_mask:0xf bank_mask:0xf bound_ctrl:1
	s_waitcnt lgkmcnt(3)
	v_pk_mul_f32 v[36:37], v[146:147], v[154:155] op_sel_hi:[1,0]
	v_pk_mul_f32 v[38:39], v[148:149], v[154:155] op_sel_hi:[1,0]
	v_add_f32_dpp v34, v34, v34 row_ror:4 row_mask:0xf bank_mask:0xf bound_ctrl:1
	v_pk_fma_f32 v[36:37], v[28:29], v[142:143], v[36:37]
	v_pk_fma_f32 v[38:39], v[30:31], v[144:145], v[38:39]
	v_add_f32_dpp v34, v34, v34 row_ror:8 row_mask:0xf bank_mask:0xf bound_ctrl:1
	ds_read_b128 v[134:137], v94 offset:14960
	ds_read_b128 v[150:153], v94 offset:15984
	v_pk_fma_f32 v[28:29], v[138:139], v[34:35], v[36:37] op_sel_hi:[1,0,1] neg_lo:[0,1,0] neg_hi:[0,1,0]
	v_pk_fma_f32 v[30:31], v[140:141], v[34:35], v[38:39] op_sel_hi:[1,0,1] neg_lo:[0,1,0] neg_hi:[0,1,0]
	v_cndmask_b32_e32 v42, v42, v34, vcc
	ds_read_b128 v[114:117], v94 offset:13856
	v_pk_mul_f32 v[24:25], v[30:31], v[112:113]
	v_pk_mul_f32 v[26:27], v[30:31], v[128:129]
	v_pk_fma_f32 v[24:25], v[28:29], v[110:111], v[24:25]
	v_pk_fma_f32 v[26:27], v[28:29], v[126:127], v[26:27]
	v_add_f32_e32 v34, v24, v25
	ds_read_b128 v[146:149], v94 offset:15728
	v_add_f32_e32 v60, v26, v27
	v_add_f32_dpp v34, v34, v34 quad_perm:[1,0,3,2] row_mask:0xf bank_mask:0xf bound_ctrl:1
	ds_read_b32 v154, v95 offset:16240
	ds_read_b128 v[142:145], v94 offset:15472
	v_add_f32_dpp v34, v34, v34 quad_perm:[2,3,0,1] row_mask:0xf bank_mask:0xf bound_ctrl:1
	s_waitcnt lgkmcnt(3)
	v_pk_mul_f32 v[36:37], v[122:123], v[130:131] op_sel_hi:[1,0]
	v_pk_mul_f32 v[38:39], v[124:125], v[130:131] op_sel_hi:[1,0]
	v_add_f32_dpp v34, v34, v34 row_ror:4 row_mask:0xf bank_mask:0xf bound_ctrl:1
	v_pk_fma_f32 v[36:37], v[28:29], v[118:119], v[36:37]
	v_pk_fma_f32 v[38:39], v[30:31], v[120:121], v[38:39]
	v_add_f32_dpp v34, v34, v34 row_ror:8 row_mask:0xf bank_mask:0xf bound_ctrl:1
	ds_read_b128 v[110:113], v94 offset:16320
	ds_read_b128 v[126:129], v94 offset:17344
	v_pk_fma_f32 v[28:29], v[114:115], v[34:35], v[36:37] op_sel_hi:[1,0,1] neg_lo:[0,1,0] neg_hi:[0,1,0]
	v_pk_fma_f32 v[30:31], v[116:117], v[34:35], v[38:39] op_sel_hi:[1,0,1] neg_lo:[0,1,0] neg_hi:[0,1,0]
	v_cndmask_b32_e64 v42, v42, v34, s[58:59]
	ds_read_b128 v[138:141], v94 offset:15216
	v_pk_mul_f32 v[24:25], v[30:31], v[136:137]
	v_pk_mul_f32 v[26:27], v[30:31], v[152:153]
	v_pk_fma_f32 v[24:25], v[28:29], v[134:135], v[24:25]
	v_pk_fma_f32 v[26:27], v[28:29], v[150:151], v[26:27]
	v_add_f32_e32 v34, v24, v25
	ds_read_b128 v[122:125], v94 offset:17088
	v_add_f32_e32 v61, v26, v27
	v_add_f32_dpp v34, v34, v34 quad_perm:[1,0,3,2] row_mask:0xf bank_mask:0xf bound_ctrl:1
	ds_read_b32 v130, v95 offset:17600
	ds_read_b128 v[118:121], v94 offset:16832
	v_add_f32_dpp v34, v34, v34 quad_perm:[2,3,0,1] row_mask:0xf bank_mask:0xf bound_ctrl:1
	s_waitcnt lgkmcnt(3)
	v_pk_mul_f32 v[36:37], v[146:147], v[154:155] op_sel_hi:[1,0]
	v_pk_mul_f32 v[38:39], v[148:149], v[154:155] op_sel_hi:[1,0]
	v_add_f32_dpp v34, v34, v34 row_ror:4 row_mask:0xf bank_mask:0xf bound_ctrl:1
	v_pk_fma_f32 v[36:37], v[28:29], v[142:143], v[36:37]
	v_pk_fma_f32 v[38:39], v[30:31], v[144:145], v[38:39]
	v_add_f32_dpp v34, v34, v34 row_ror:8 row_mask:0xf bank_mask:0xf bound_ctrl:1
	ds_read_b128 v[134:137], v94 offset:17680
	ds_read_b128 v[150:153], v94 offset:18704
	v_pk_fma_f32 v[28:29], v[138:139], v[34:35], v[36:37] op_sel_hi:[1,0,1] neg_lo:[0,1,0] neg_hi:[0,1,0]
	v_pk_fma_f32 v[30:31], v[140:141], v[34:35], v[38:39] op_sel_hi:[1,0,1] neg_lo:[0,1,0] neg_hi:[0,1,0]
	v_cndmask_b32_e64 v42, v42, v34, s[60:61]
	ds_read_b128 v[114:117], v94 offset:16576
	v_pk_mul_f32 v[24:25], v[30:31], v[112:113]
	v_pk_mul_f32 v[26:27], v[30:31], v[128:129]
	v_pk_fma_f32 v[24:25], v[28:29], v[110:111], v[24:25]
	v_pk_fma_f32 v[26:27], v[28:29], v[126:127], v[26:27]
	v_add_f32_e32 v34, v24, v25
	ds_read_b128 v[146:149], v94 offset:18448
	v_add_f32_e32 v62, v26, v27
	v_add_f32_dpp v34, v34, v34 quad_perm:[1,0,3,2] row_mask:0xf bank_mask:0xf bound_ctrl:1
	ds_read_b32 v154, v95 offset:18960
	ds_read_b128 v[142:145], v94 offset:18192
	v_add_f32_dpp v34, v34, v34 quad_perm:[2,3,0,1] row_mask:0xf bank_mask:0xf bound_ctrl:1
	s_waitcnt lgkmcnt(3)
	v_pk_mul_f32 v[36:37], v[122:123], v[130:131] op_sel_hi:[1,0]
	v_pk_mul_f32 v[38:39], v[124:125], v[130:131] op_sel_hi:[1,0]
	v_add_f32_dpp v34, v34, v34 row_ror:4 row_mask:0xf bank_mask:0xf bound_ctrl:1
	v_pk_fma_f32 v[36:37], v[28:29], v[118:119], v[36:37]
	v_pk_fma_f32 v[38:39], v[30:31], v[120:121], v[38:39]
	v_add_f32_dpp v34, v34, v34 row_ror:8 row_mask:0xf bank_mask:0xf bound_ctrl:1
	ds_read_b128 v[110:113], v94 offset:19040
	ds_read_b128 v[126:129], v94 offset:20064
	v_pk_fma_f32 v[28:29], v[114:115], v[34:35], v[36:37] op_sel_hi:[1,0,1] neg_lo:[0,1,0] neg_hi:[0,1,0]
	v_pk_fma_f32 v[30:31], v[116:117], v[34:35], v[38:39] op_sel_hi:[1,0,1] neg_lo:[0,1,0] neg_hi:[0,1,0]
	v_cndmask_b32_e64 v42, v42, v34, s[62:63]
	ds_read_b128 v[138:141], v94 offset:17936
	v_pk_mul_f32 v[24:25], v[30:31], v[136:137]
	v_pk_mul_f32 v[26:27], v[30:31], v[152:153]
	v_pk_fma_f32 v[24:25], v[28:29], v[134:135], v[24:25]
	v_pk_fma_f32 v[26:27], v[28:29], v[150:151], v[26:27]
	v_add_f32_e32 v34, v24, v25
	ds_read_b128 v[122:125], v94 offset:19808
	v_add_f32_e32 v63, v26, v27
	v_add_f32_dpp v34, v34, v34 quad_perm:[1,0,3,2] row_mask:0xf bank_mask:0xf bound_ctrl:1
	ds_read_b32 v130, v95 offset:20320
	ds_read_b128 v[118:121], v94 offset:19552
	v_add_f32_dpp v34, v34, v34 quad_perm:[2,3,0,1] row_mask:0xf bank_mask:0xf bound_ctrl:1
	s_waitcnt lgkmcnt(3)
	v_pk_mul_f32 v[36:37], v[146:147], v[154:155] op_sel_hi:[1,0]
	v_pk_mul_f32 v[38:39], v[148:149], v[154:155] op_sel_hi:[1,0]
	v_add_f32_dpp v34, v34, v34 row_ror:4 row_mask:0xf bank_mask:0xf bound_ctrl:1
	v_pk_fma_f32 v[36:37], v[28:29], v[142:143], v[36:37]
	v_pk_fma_f32 v[38:39], v[30:31], v[144:145], v[38:39]
	v_add_f32_dpp v34, v34, v34 row_ror:8 row_mask:0xf bank_mask:0xf bound_ctrl:1
	ds_read_b128 v[134:137], v94 offset:20400
	ds_read_b128 v[150:153], v94 offset:21424
	v_pk_fma_f32 v[28:29], v[138:139], v[34:35], v[36:37] op_sel_hi:[1,0,1] neg_lo:[0,1,0] neg_hi:[0,1,0]
	v_pk_fma_f32 v[30:31], v[140:141], v[34:35], v[38:39] op_sel_hi:[1,0,1] neg_lo:[0,1,0] neg_hi:[0,1,0]
	v_cndmask_b32_e64 v42, v42, v34, s[66:67]
	ds_read_b128 v[114:117], v94 offset:19296
	v_pk_mul_f32 v[24:25], v[30:31], v[112:113]
	v_pk_mul_f32 v[26:27], v[30:31], v[128:129]
	v_pk_fma_f32 v[24:25], v[28:29], v[110:111], v[24:25]
	v_pk_fma_f32 v[26:27], v[28:29], v[126:127], v[26:27]
	v_add_f32_e32 v34, v24, v25
	ds_read_b128 v[146:149], v94 offset:21168
	v_add_f32_e32 v64, v26, v27
	v_add_f32_dpp v34, v34, v34 quad_perm:[1,0,3,2] row_mask:0xf bank_mask:0xf bound_ctrl:1
	ds_read_b32 v154, v95 offset:21680
	ds_read_b128 v[142:145], v94 offset:20912
	v_add_f32_dpp v34, v34, v34 quad_perm:[2,3,0,1] row_mask:0xf bank_mask:0xf bound_ctrl:1
	s_waitcnt lgkmcnt(3)
	v_pk_mul_f32 v[36:37], v[122:123], v[130:131] op_sel_hi:[1,0]
	v_pk_mul_f32 v[38:39], v[124:125], v[130:131] op_sel_hi:[1,0]
	v_add_f32_dpp v34, v34, v34 row_ror:4 row_mask:0xf bank_mask:0xf bound_ctrl:1
	v_pk_fma_f32 v[36:37], v[28:29], v[118:119], v[36:37]
	v_pk_fma_f32 v[38:39], v[30:31], v[120:121], v[38:39]
	v_add_f32_dpp v34, v34, v34 row_ror:8 row_mask:0xf bank_mask:0xf bound_ctrl:1
	v_pk_fma_f32 v[28:29], v[114:115], v[34:35], v[36:37] op_sel_hi:[1,0,1] neg_lo:[0,1,0] neg_hi:[0,1,0]
	v_pk_fma_f32 v[30:31], v[116:117], v[34:35], v[38:39] op_sel_hi:[1,0,1] neg_lo:[0,1,0] neg_hi:[0,1,0]
	v_cndmask_b32_e64 v42, v42, v34, s[64:65]
	ds_read_b128 v[138:141], v94 offset:20656
	v_pk_mul_f32 v[24:25], v[30:31], v[136:137]
	v_pk_mul_f32 v[26:27], v[30:31], v[152:153]
	v_pk_fma_f32 v[24:25], v[28:29], v[134:135], v[24:25]
	v_pk_fma_f32 v[26:27], v[28:29], v[150:151], v[26:27]
	v_add_f32_e32 v34, v24, v25
	v_lshl_add_u64 v[70:71], v[70:71], 0, s[2:3]
	v_add_f32_e32 v65, v26, v27
	v_add_f32_dpp v34, v34, v34 quad_perm:[1,0,3,2] row_mask:0xf bank_mask:0xf bound_ctrl:1
	v_lshl_add_u64 v[72:73], v[72:73], 0, s[20:21]
	v_lshl_add_u64 v[74:75], v[74:75], 0, s[20:21]
	v_add_f32_dpp v34, v34, v34 quad_perm:[2,3,0,1] row_mask:0xf bank_mask:0xf bound_ctrl:1
	s_waitcnt lgkmcnt(0)
	v_pk_mul_f32 v[36:37], v[146:147], v[154:155] op_sel_hi:[1,0]
	v_pk_mul_f32 v[38:39], v[148:149], v[154:155] op_sel_hi:[1,0]
	v_add_f32_dpp v34, v34, v34 row_ror:4 row_mask:0xf bank_mask:0xf bound_ctrl:1
	v_pk_fma_f32 v[36:37], v[28:29], v[142:143], v[36:37]
	v_pk_fma_f32 v[38:39], v[30:31], v[144:145], v[38:39]
	v_add_f32_dpp v34, v34, v34 row_ror:8 row_mask:0xf bank_mask:0xf bound_ctrl:1
	v_pk_fma_f32 v[28:29], v[138:139], v[34:35], v[36:37] op_sel_hi:[1,0,1] neg_lo:[0,1,0] neg_hi:[0,1,0]
	v_pk_fma_f32 v[30:31], v[140:141], v[34:35], v[38:39] op_sel_hi:[1,0,1] neg_lo:[0,1,0] neg_hi:[0,1,0]
	v_cndmask_b32_e64 v42, v42, v34, s[68:69]
	v_add_f32_dpp v50, v50, v50 row_ror:8 row_mask:0xf bank_mask:0xf bound_ctrl:1
	v_add_f32_dpp v51, v51, v51 row_ror:8 row_mask:0xf bank_mask:0xf bound_ctrl:1
	v_add_f32_dpp v52, v52, v52 row_ror:8 row_mask:0xf bank_mask:0xf bound_ctrl:1
	v_add_f32_dpp v53, v53, v53 row_ror:8 row_mask:0xf bank_mask:0xf bound_ctrl:1
	v_add_f32_dpp v54, v54, v54 row_ror:8 row_mask:0xf bank_mask:0xf bound_ctrl:1
	v_add_f32_dpp v55, v55, v55 row_ror:8 row_mask:0xf bank_mask:0xf bound_ctrl:1
	v_add_f32_dpp v56, v56, v56 row_ror:8 row_mask:0xf bank_mask:0xf bound_ctrl:1
	v_add_f32_dpp v57, v57, v57 row_ror:8 row_mask:0xf bank_mask:0xf bound_ctrl:1
	v_add_f32_dpp v50, v58, v58 row_ror:8 row_mask:0xf bank_mask:0xc bound_ctrl:1
	v_add_f32_dpp v51, v59, v59 row_ror:8 row_mask:0xf bank_mask:0xc bound_ctrl:1
	v_add_f32_dpp v52, v60, v60 row_ror:8 row_mask:0xf bank_mask:0xc bound_ctrl:1
	v_add_f32_dpp v53, v61, v61 row_ror:8 row_mask:0xf bank_mask:0xc bound_ctrl:1
	v_add_f32_dpp v54, v62, v62 row_ror:8 row_mask:0xf bank_mask:0xc bound_ctrl:1
	v_add_f32_dpp v55, v63, v63 row_ror:8 row_mask:0xf bank_mask:0xc bound_ctrl:1
	v_add_f32_dpp v56, v64, v64 row_ror:8 row_mask:0xf bank_mask:0xc bound_ctrl:1
	v_add_f32_dpp v57, v65, v65 row_ror:8 row_mask:0xf bank_mask:0xc bound_ctrl:1
	s_mov_b32 s2, 0xcccccccc
	s_mov_b32 s3, 0xcccccccc
	v_add_f32_dpp v50, v50, v50 row_half_mirror row_mask:0xf bank_mask:0x5 bound_ctrl:1
	v_add_f32_dpp v51, v51, v51 row_half_mirror row_mask:0xf bank_mask:0x5 bound_ctrl:1
	v_add_f32_dpp v52, v52, v52 row_half_mirror row_mask:0xf bank_mask:0x5 bound_ctrl:1
	v_add_f32_dpp v53, v53, v53 row_half_mirror row_mask:0xf bank_mask:0x5 bound_ctrl:1
	s_mov_b32 s20, 0xaaaaaaaa
	s_mov_b32 s21, 0xaaaaaaaa
	v_add_f32_dpp v50, v54, v54 row_half_mirror row_mask:0xf bank_mask:0xa bound_ctrl:1
	v_add_f32_dpp v51, v55, v55 row_half_mirror row_mask:0xf bank_mask:0xa bound_ctrl:1
	v_add_f32_dpp v52, v56, v56 row_half_mirror row_mask:0xf bank_mask:0xa bound_ctrl:1
	v_add_f32_dpp v53, v57, v57 row_half_mirror row_mask:0xf bank_mask:0xa bound_ctrl:1
	v_cndmask_b32_e64 v58, v52, v50, s[2:3]
	v_cndmask_b32_e64 v59, v53, v51, s[2:3]
	v_cndmask_b32_e64 v60, v50, v52, s[2:3]
	v_cndmask_b32_e64 v61, v51, v53, s[2:3]
	v_add_f32_dpp v50, v58, v60 quad_perm:[2,3,0,1] row_mask:0xf bank_mask:0xf bound_ctrl:1
	v_add_f32_dpp v51, v59, v61 quad_perm:[2,3,0,1] row_mask:0xf bank_mask:0xf bound_ctrl:1
	v_lshl_add_u64 v[24:25], v[68:69], 0, s[0:1]
	s_add_u32 s0, s0, 0x1000
	s_addc_u32 s1, s1, 0
	v_cndmask_b32_e64 v58, v51, v50, s[20:21]
	v_cndmask_b32_e64 v60, v50, v51, s[20:21]
	s_add_i32 s24, s24, 1
	s_cmp_lg_u32 s0, 0xac000
	v_add_f32_dpp v43, v58, v60 quad_perm:[1,0,3,2] row_mask:0xf bank_mask:0xf bound_ctrl:1
	v_fma_f32 v40, -v44, v42, v43
	v_fmac_f32_e32 v40, v48, v45
	global_store_dword v[24:25], v40, off
	s_barrier
	s_cbranch_scc0 .LBB0_81

.LBB0_151:
	s_bitcmp1_b32 s24, 0
	s_cselect_b32 s2, 0x5500, 0
	v_lshl_or_b32 v94, v93, 2, s2
	v_lshl_add_u32 v95, v0, 2, s2
	v_mov_b32_e32 v96, s2
	v_mul_u32_u24_e32 v46, 0x154, v93
	v_add_u32_e32 v47, v46, v96
	v_add_u32_e32 v46, v46, v95
	ds_read_b64 v[44:45], v47 offset:1344
	ds_read_b32 v48, v46 offset:1280
	ds_read_b128 v[110:113], v94
	ds_read_b128 v[126:129], v94 offset:1024
	ds_read_b128 v[122:125], v94 offset:768
	ds_read_b32 v130, v95 offset:1280
	ds_read_b128 v[118:121], v94 offset:512
	ds_read_b128 v[114:117], v94 offset:256
	ds_read_b128 v[134:137], v94 offset:1360
	ds_read_b128 v[150:153], v94 offset:2384
	s_mov_b64 s[2:3], 0x100
	s_mov_b64 s[20:21], 0x800
	s_waitcnt lgkmcnt(6)
	v_pk_mul_f32 v[24:25], v[30:31], v[112:113]
	v_pk_mul_f32 v[26:27], v[30:31], v[128:129]
	v_pk_fma_f32 v[24:25], v[28:29], v[110:111], v[24:25]
	v_pk_fma_f32 v[26:27], v[28:29], v[126:127], v[26:27]
	v_add_f32_e32 v34, v24, v25
	ds_read_b128 v[146:149], v94 offset:2128
	v_add_f32_e32 v50, v26, v27
	v_add_f32_dpp v34, v34, v34 quad_perm:[1,0,3,2] row_mask:0xf bank_mask:0xf bound_ctrl:1
	ds_read_b32 v154, v95 offset:2640
	ds_read_b128 v[142:145], v94 offset:1872
	v_add_f32_dpp v34, v34, v34 quad_perm:[2,3,0,1] row_mask:0xf bank_mask:0xf bound_ctrl:1
	s_waitcnt lgkmcnt(3)
	v_pk_mul_f32 v[36:37], v[122:123], v[130:131] op_sel_hi:[1,0]
	v_pk_mul_f32 v[38:39], v[124:125], v[130:131] op_sel_hi:[1,0]
	v_add_f32_dpp v34, v34, v34 row_ror:4 row_mask:0xf bank_mask:0xf bound_ctrl:1
	v_pk_fma_f32 v[36:37], v[28:29], v[118:119], v[36:37]
	v_pk_fma_f32 v[38:39], v[30:31], v[120:121], v[38:39]
	v_add_f32_dpp v34, v34, v34 row_ror:8 row_mask:0xf bank_mask:0xf bound_ctrl:1
	ds_read_b128 v[110:113], v94 offset:2720
	ds_read_b128 v[126:129], v94 offset:3744
	v_pk_fma_f32 v[28:29], v[114:115], v[34:35], v[36:37] op_sel_hi:[1,0,1] neg_lo:[0,1,0] neg_hi:[0,1,0]
	v_pk_fma_f32 v[30:31], v[116:117], v[34:35], v[38:39] op_sel_hi:[1,0,1] neg_lo:[0,1,0] neg_hi:[0,1,0]
	v_cndmask_b32_e64 v42, 0, v34, s[72:73]
	ds_read_b128 v[138:141], v94 offset:1616
	v_pk_mul_f32 v[24:25], v[30:31], v[136:137]
	v_pk_mul_f32 v[26:27], v[30:31], v[152:153]
	v_pk_fma_f32 v[24:25], v[28:29], v[134:135], v[24:25]
	v_pk_fma_f32 v[26:27], v[28:29], v[150:151], v[26:27]
	v_add_f32_e32 v34, v24, v25
	ds_read_b128 v[122:125], v94 offset:3488
	v_add_f32_e32 v51, v26, v27
	v_add_f32_dpp v34, v34, v34 quad_perm:[1,0,3,2] row_mask:0xf bank_mask:0xf bound_ctrl:1
	ds_read_b32 v130, v95 offset:4000
	ds_read_b128 v[118:121], v94 offset:3232
	v_add_f32_dpp v34, v34, v34 quad_perm:[2,3,0,1] row_mask:0xf bank_mask:0xf bound_ctrl:1
	s_waitcnt lgkmcnt(3)
	v_pk_mul_f32 v[36:37], v[146:147], v[154:155] op_sel_hi:[1,0]
	v_pk_mul_f32 v[38:39], v[148:149], v[154:155] op_sel_hi:[1,0]
	v_add_f32_dpp v34, v34, v34 row_ror:4 row_mask:0xf bank_mask:0xf bound_ctrl:1
	v_pk_fma_f32 v[36:37], v[28:29], v[142:143], v[36:37]
	v_pk_fma_f32 v[38:39], v[30:31], v[144:145], v[38:39]
	v_add_f32_dpp v34, v34, v34 row_ror:8 row_mask:0xf bank_mask:0xf bound_ctrl:1
	ds_read_b128 v[134:137], v94 offset:4080
	ds_read_b128 v[150:153], v94 offset:5104
	v_pk_fma_f32 v[28:29], v[138:139], v[34:35], v[36:37] op_sel_hi:[1,0,1] neg_lo:[0,1,0] neg_hi:[0,1,0]
	v_pk_fma_f32 v[30:31], v[140:141], v[34:35], v[38:39] op_sel_hi:[1,0,1] neg_lo:[0,1,0] neg_hi:[0,1,0]
	v_cndmask_b32_e64 v42, v42, v34, s[30:31]
	ds_read_b128 v[114:117], v94 offset:2976
	v_pk_mul_f32 v[24:25], v[30:31], v[112:113]
	v_pk_mul_f32 v[26:27], v[30:31], v[128:129]
	v_pk_fma_f32 v[24:25], v[28:29], v[110:111], v[24:25]
	v_pk_fma_f32 v[26:27], v[28:29], v[126:127], v[26:27]
	v_add_f32_e32 v34, v24, v25
	ds_read_b128 v[146:149], v94 offset:4848
	v_add_f32_e32 v52, v26, v27
	v_add_f32_dpp v34, v34, v34 quad_perm:[1,0,3,2] row_mask:0xf bank_mask:0xf bound_ctrl:1
	ds_read_b32 v154, v95 offset:5360
	ds_read_b128 v[142:145], v94 offset:4592
	v_add_f32_dpp v34, v34, v34 quad_perm:[2,3,0,1] row_mask:0xf bank_mask:0xf bound_ctrl:1
	s_waitcnt lgkmcnt(3)
	v_pk_mul_f32 v[36:37], v[122:123], v[130:131] op_sel_hi:[1,0]
	v_pk_mul_f32 v[38:39], v[124:125], v[130:131] op_sel_hi:[1,0]
	v_add_f32_dpp v34, v34, v34 row_ror:4 row_mask:0xf bank_mask:0xf bound_ctrl:1
	v_pk_fma_f32 v[36:37], v[28:29], v[118:119], v[36:37]
	v_pk_fma_f32 v[38:39], v[30:31], v[120:121], v[38:39]
	v_add_f32_dpp v34, v34, v34 row_ror:8 row_mask:0xf bank_mask:0xf bound_ctrl:1
	ds_read_b128 v[110:113], v94 offset:5440
	ds_read_b128 v[126:129], v94 offset:6464
	v_pk_fma_f32 v[28:29], v[114:115], v[34:35], v[36:37] op_sel_hi:[1,0,1] neg_lo:[0,1,0] neg_hi:[0,1,0]
	v_pk_fma_f32 v[30:31], v[116:117], v[34:35], v[38:39] op_sel_hi:[1,0,1] neg_lo:[0,1,0] neg_hi:[0,1,0]
	v_cndmask_b32_e64 v42, v42, v34, s[70:71]
	ds_read_b128 v[138:141], v94 offset:4336
	v_pk_mul_f32 v[24:25], v[30:31], v[136:137]
	v_pk_mul_f32 v[26:27], v[30:31], v[152:153]
	v_pk_fma_f32 v[24:25], v[28:29], v[134:135], v[24:25]
	v_pk_fma_f32 v[26:27], v[28:29], v[150:151], v[26:27]
	v_add_f32_e32 v34, v24, v25
	ds_read_b128 v[122:125], v94 offset:6208
	v_add_f32_e32 v53, v26, v27
	v_add_f32_dpp v34, v34, v34 quad_perm:[1,0,3,2] row_mask:0xf bank_mask:0xf bound_ctrl:1
	ds_read_b32 v130, v95 offset:6720
	ds_read_b128 v[118:121], v94 offset:5952
	v_add_f32_dpp v34, v34, v34 quad_perm:[2,3,0,1] row_mask:0xf bank_mask:0xf bound_ctrl:1
	s_waitcnt lgkmcnt(3)
	v_pk_mul_f32 v[36:37], v[146:147], v[154:155] op_sel_hi:[1,0]
	v_pk_mul_f32 v[38:39], v[148:149], v[154:155] op_sel_hi:[1,0]
	v_add_f32_dpp v34, v34, v34 row_ror:4 row_mask:0xf bank_mask:0xf bound_ctrl:1
	v_pk_fma_f32 v[36:37], v[28:29], v[142:143], v[36:37]
	v_pk_fma_f32 v[38:39], v[30:31], v[144:145], v[38:39]
	v_add_f32_dpp v34, v34, v34 row_ror:8 row_mask:0xf bank_mask:0xf bound_ctrl:1
	ds_read_b128 v[134:137], v94 offset:6800
	ds_read_b128 v[150:153], v94 offset:7824
	v_pk_fma_f32 v[28:29], v[138:139], v[34:35], v[36:37] op_sel_hi:[1,0,1] neg_lo:[0,1,0] neg_hi:[0,1,0]
	v_pk_fma_f32 v[30:31], v[140:141], v[34:35], v[38:39] op_sel_hi:[1,0,1] neg_lo:[0,1,0] neg_hi:[0,1,0]
	v_cndmask_b32_e64 v42, v42, v34, s[40:41]
	ds_read_b128 v[114:117], v94 offset:5696
	v_pk_mul_f32 v[24:25], v[30:31], v[112:113]
	v_pk_mul_f32 v[26:27], v[30:31], v[128:129]
	v_pk_fma_f32 v[24:25], v[28:29], v[110:111], v[24:25]
	v_pk_fma_f32 v[26:27], v[28:29], v[126:127], v[26:27]
	v_add_f32_e32 v34, v24, v25
	ds_read_b128 v[146:149], v94 offset:7568
	v_add_f32_e32 v54, v26, v27
	v_add_f32_dpp v34, v34, v34 quad_perm:[1,0,3,2] row_mask:0xf bank_mask:0xf bound_ctrl:1
	ds_read_b32 v154, v95 offset:8080
	ds_read_b128 v[142:145], v94 offset:7312
	v_add_f32_dpp v34, v34, v34 quad_perm:[2,3,0,1] row_mask:0xf bank_mask:0xf bound_ctrl:1
	s_waitcnt lgkmcnt(3)
	v_pk_mul_f32 v[36:37], v[122:123], v[130:131] op_sel_hi:[1,0]
	v_pk_mul_f32 v[38:39], v[124:125], v[130:131] op_sel_hi:[1,0]
	v_add_f32_dpp v34, v34, v34 row_ror:4 row_mask:0xf bank_mask:0xf bound_ctrl:1
	v_pk_fma_f32 v[36:37], v[28:29], v[118:119], v[36:37]
	v_pk_fma_f32 v[38:39], v[30:31], v[120:121], v[38:39]
	v_add_f32_dpp v34, v34, v34 row_ror:8 row_mask:0xf bank_mask:0xf bound_ctrl:1
	ds_read_b128 v[110:113], v94 offset:8160
	ds_read_b128 v[126:129], v94 offset:9184
	v_pk_fma_f32 v[28:29], v[114:115], v[34:35], v[36:37] op_sel_hi:[1,0,1] neg_lo:[0,1,0] neg_hi:[0,1,0]
	v_pk_fma_f32 v[30:31], v[116:117], v[34:35], v[38:39] op_sel_hi:[1,0,1] neg_lo:[0,1,0] neg_hi:[0,1,0]
	v_cndmask_b32_e64 v42, v42, v34, s[42:43]
	ds_read_b128 v[138:141], v94 offset:7056
	v_pk_mul_f32 v[24:25], v[30:31], v[136:137]
	v_pk_mul_f32 v[26:27], v[30:31], v[152:153]
	v_pk_fma_f32 v[24:25], v[28:29], v[134:135], v[24:25]
	v_pk_fma_f32 v[26:27], v[28:29], v[150:151], v[26:27]
	v_add_f32_e32 v34, v24, v25
	ds_read_b128 v[122:125], v94 offset:8928
	v_add_f32_e32 v55, v26, v27
	v_add_f32_dpp v34, v34, v34 quad_perm:[1,0,3,2] row_mask:0xf bank_mask:0xf bound_ctrl:1
	ds_read_b32 v130, v95 offset:9440
	ds_read_b128 v[118:121], v94 offset:8672
	v_add_f32_dpp v34, v34, v34 quad_perm:[2,3,0,1] row_mask:0xf bank_mask:0xf bound_ctrl:1
	s_waitcnt lgkmcnt(3)
	v_pk_mul_f32 v[36:37], v[146:147], v[154:155] op_sel_hi:[1,0]
	v_pk_mul_f32 v[38:39], v[148:149], v[154:155] op_sel_hi:[1,0]
	v_add_f32_dpp v34, v34, v34 row_ror:4 row_mask:0xf bank_mask:0xf bound_ctrl:1
	v_pk_fma_f32 v[36:37], v[28:29], v[142:143], v[36:37]
	v_pk_fma_f32 v[38:39], v[30:31], v[144:145], v[38:39]
	v_add_f32_dpp v34, v34, v34 row_ror:8 row_mask:0xf bank_mask:0xf bound_ctrl:1
	ds_read_b128 v[134:137], v94 offset:9520
	ds_read_b128 v[150:153], v94 offset:10544
	v_pk_fma_f32 v[28:29], v[138:139], v[34:35], v[36:37] op_sel_hi:[1,0,1] neg_lo:[0,1,0] neg_hi:[0,1,0]
	v_pk_fma_f32 v[30:31], v[140:141], v[34:35], v[38:39] op_sel_hi:[1,0,1] neg_lo:[0,1,0] neg_hi:[0,1,0]
	v_cndmask_b32_e64 v42, v42, v34, s[44:45]
	ds_read_b128 v[114:117], v94 offset:8416
	v_pk_mul_f32 v[24:25], v[30:31], v[112:113]
	v_pk_mul_f32 v[26:27], v[30:31], v[128:129]
	v_pk_fma_f32 v[24:25], v[28:29], v[110:111], v[24:25]
	v_pk_fma_f32 v[26:27], v[28:29], v[126:127], v[26:27]
	v_add_f32_e32 v34, v24, v25
	ds_read_b128 v[146:149], v94 offset:10288
	v_add_f32_e32 v56, v26, v27
	v_add_f32_dpp v34, v34, v34 quad_perm:[1,0,3,2] row_mask:0xf bank_mask:0xf bound_ctrl:1
	ds_read_b32 v154, v95 offset:10800
	ds_read_b128 v[142:145], v94 offset:10032
	v_add_f32_dpp v34, v34, v34 quad_perm:[2,3,0,1] row_mask:0xf bank_mask:0xf bound_ctrl:1
	s_waitcnt lgkmcnt(3)
	v_pk_mul_f32 v[36:37], v[122:123], v[130:131] op_sel_hi:[1,0]
	v_pk_mul_f32 v[38:39], v[124:125], v[130:131] op_sel_hi:[1,0]
	v_add_f32_dpp v34, v34, v34 row_ror:4 row_mask:0xf bank_mask:0xf bound_ctrl:1
	v_pk_fma_f32 v[36:37], v[28:29], v[118:119], v[36:37]
	v_pk_fma_f32 v[38:39], v[30:31], v[120:121], v[38:39]
	v_add_f32_dpp v34, v34, v34 row_ror:8 row_mask:0xf bank_mask:0xf bound_ctrl:1
	ds_read_b128 v[110:113], v94 offset:10880
	ds_read_b128 v[126:129], v94 offset:11904
	v_pk_fma_f32 v[28:29], v[114:115], v[34:35], v[36:37] op_sel_hi:[1,0,1] neg_lo:[0,1,0] neg_hi:[0,1,0]
	v_pk_fma_f32 v[30:31], v[116:117], v[34:35], v[38:39] op_sel_hi:[1,0,1] neg_lo:[0,1,0] neg_hi:[0,1,0]
	v_cndmask_b32_e64 v42, v42, v34, s[46:47]
	ds_read_b128 v[138:141], v94 offset:9776
	v_pk_mul_f32 v[24:25], v[30:31], v[136:137]
	v_pk_mul_f32 v[26:27], v[30:31], v[152:153]
	v_pk_fma_f32 v[24:25], v[28:29], v[134:135], v[24:25]
	v_pk_fma_f32 v[26:27], v[28:29], v[150:151], v[26:27]
	v_add_f32_e32 v34, v24, v25
	ds_read_b128 v[122:125], v94 offset:11648
	v_add_f32_e32 v57, v26, v27
	v_add_f32_dpp v34, v34, v34 quad_perm:[1,0,3,2] row_mask:0xf bank_mask:0xf bound_ctrl:1
	ds_read_b32 v130, v95 offset:12160
	ds_read_b128 v[118:121], v94 offset:11392
	v_add_f32_dpp v34, v34, v34 quad_perm:[2,3,0,1] row_mask:0xf bank_mask:0xf bound_ctrl:1
	s_waitcnt lgkmcnt(3)
	v_pk_mul_f32 v[36:37], v[146:147], v[154:155] op_sel_hi:[1,0]
	v_pk_mul_f32 v[38:39], v[148:149], v[154:155] op_sel_hi:[1,0]
	v_add_f32_dpp v34, v34, v34 row_ror:4 row_mask:0xf bank_mask:0xf bound_ctrl:1
	v_pk_fma_f32 v[36:37], v[28:29], v[142:143], v[36:37]
	v_pk_fma_f32 v[38:39], v[30:31], v[144:145], v[38:39]
	v_add_f32_dpp v34, v34, v34 row_ror:8 row_mask:0xf bank_mask:0xf bound_ctrl:1
	ds_read_b128 v[134:137], v94 offset:12240
	ds_read_b128 v[150:153], v94 offset:13264
	v_pk_fma_f32 v[28:29], v[138:139], v[34:35], v[36:37] op_sel_hi:[1,0,1] neg_lo:[0,1,0] neg_hi:[0,1,0]
	v_pk_fma_f32 v[30:31], v[140:141], v[34:35], v[38:39] op_sel_hi:[1,0,1] neg_lo:[0,1,0] neg_hi:[0,1,0]
	v_cndmask_b32_e64 v42, v42, v34, s[58:59]
	ds_read_b128 v[114:117], v94 offset:11136
	v_pk_mul_f32 v[24:25], v[30:31], v[112:113]
	v_pk_mul_f32 v[26:27], v[30:31], v[128:129]
	v_pk_fma_f32 v[24:25], v[28:29], v[110:111], v[24:25]
	v_pk_fma_f32 v[26:27], v[28:29], v[126:127], v[26:27]
	v_add_f32_e32 v34, v24, v25
	ds_read_b128 v[146:149], v94 offset:13008
	v_add_f32_e32 v58, v26, v27
	v_add_f32_dpp v34, v34, v34 quad_perm:[1,0,3,2] row_mask:0xf bank_mask:0xf bound_ctrl:1
	ds_read_b32 v154, v95 offset:13520
	ds_read_b128 v[142:145], v94 offset:12752
	v_add_f32_dpp v34, v34, v34 quad_perm:[2,3,0,1] row_mask:0xf bank_mask:0xf bound_ctrl:1
	s_waitcnt lgkmcnt(3)
	v_pk_mul_f32 v[36:37], v[122:123], v[130:131] op_sel_hi:[1,0]
	v_pk_mul_f32 v[38:39], v[124:125], v[130:131] op_sel_hi:[1,0]
	v_add_f32_dpp v34, v34, v34 row_ror:4 row_mask:0xf bank_mask:0xf bound_ctrl:1
	v_pk_fma_f32 v[36:37], v[28:29], v[118:119], v[36:37]
	v_pk_fma_f32 v[38:39], v[30:31], v[120:121], v[38:39]
	v_add_f32_dpp v34, v34, v34 row_ror:8 row_mask:0xf bank_mask:0xf bound_ctrl:1
	ds_read_b128 v[110:113], v94 offset:13600
	ds_read_b128 v[126:129], v94 offset:14624
	v_pk_fma_f32 v[28:29], v[114:115], v[34:35], v[36:37] op_sel_hi:[1,0,1] neg_lo:[0,1,0] neg_hi:[0,1,0]
	v_pk_fma_f32 v[30:31], v[116:117], v[34:35], v[38:39] op_sel_hi:[1,0,1] neg_lo:[0,1,0] neg_hi:[0,1,0]
	v_cndmask_b32_e64 v42, v42, v34, s[60:61]
	ds_read_b128 v[138:141], v94 offset:12496
	v_pk_mul_f32 v[24:25], v[30:31], v[136:137]
	v_pk_mul_f32 v[26:27], v[30:31], v[152:153]
	v_pk_fma_f32 v[24:25], v[28:29], v[134:135], v[24:25]
	v_pk_fma_f32 v[26:27], v[28:29], v[150:151], v[26:27]
	v_add_f32_e32 v34, v24, v25
	ds_read_b128 v[122:125], v94 offset:14368
	v_add_f32_e32 v59, v26, v27
	v_add_f32_dpp v34, v34, v34 quad_perm:[1,0,3,2] row_mask:0xf bank_mask:0xf bound_ctrl:1
	ds_read_b32 v130, v95 offset:14880
	ds_read_b128 v[118:121], v94 offset:14112
	v_add_f32_dpp v34, v34, v34 quad_perm:[2,3,0,1] row_mask:0xf bank_mask:0xf bound_ctrl:1
	s_waitcnt lgkmcnt(3)
	v_pk_mul_f32 v[36:37], v[146:147], v[154:155] op_sel_hi:[1,0]
	v_pk_mul_f32 v[38:39], v[148:149], v[154:155] op_sel_hi:[1,0]
	v_add_f32_dpp v34, v34, v34 row_ror:4 row_mask:0xf bank_mask:0xf bound_ctrl:1
	v_pk_fma_f32 v[36:37], v[28:29], v[142:143], v[36:37]
	v_pk_fma_f32 v[38:39], v[30:31], v[144:145], v[38:39]
	v_add_f32_dpp v34, v34, v34 row_ror:8 row_mask:0xf bank_mask:0xf bound_ctrl:1
	ds_read_b128 v[134:137], v94 offset:14960
	ds_read_b128 v[150:153], v94 offset:15984
	v_pk_fma_f32 v[28:29], v[138:139], v[34:35], v[36:37] op_sel_hi:[1,0,1] neg_lo:[0,1,0] neg_hi:[0,1,0]
	v_pk_fma_f32 v[30:31], v[140:141], v[34:35], v[38:39] op_sel_hi:[1,0,1] neg_lo:[0,1,0] neg_hi:[0,1,0]
	v_cndmask_b32_e64 v42, v42, v34, s[62:63]
	ds_read_b128 v[114:117], v94 offset:13856
	v_pk_mul_f32 v[24:25], v[30:31], v[112:113]
	v_pk_mul_f32 v[26:27], v[30:31], v[128:129]
	v_pk_fma_f32 v[24:25], v[28:29], v[110:111], v[24:25]
	v_pk_fma_f32 v[26:27], v[28:29], v[126:127], v[26:27]
	v_add_f32_e32 v34, v24, v25
	ds_read_b128 v[146:149], v94 offset:15728
	v_add_f32_e32 v60, v26, v27
	v_add_f32_dpp v34, v34, v34 quad_perm:[1,0,3,2] row_mask:0xf bank_mask:0xf bound_ctrl:1
	ds_read_b32 v154, v95 offset:16240
	ds_read_b128 v[142:145], v94 offset:15472
	v_add_f32_dpp v34, v34, v34 quad_perm:[2,3,0,1] row_mask:0xf bank_mask:0xf bound_ctrl:1
	s_waitcnt lgkmcnt(3)
	v_pk_mul_f32 v[36:37], v[122:123], v[130:131] op_sel_hi:[1,0]
	v_pk_mul_f32 v[38:39], v[124:125], v[130:131] op_sel_hi:[1,0]
	v_add_f32_dpp v34, v34, v34 row_ror:4 row_mask:0xf bank_mask:0xf bound_ctrl:1
	v_pk_fma_f32 v[36:37], v[28:29], v[118:119], v[36:37]
	v_pk_fma_f32 v[38:39], v[30:31], v[120:121], v[38:39]
	v_add_f32_dpp v34, v34, v34 row_ror:8 row_mask:0xf bank_mask:0xf bound_ctrl:1
	ds_read_b128 v[110:113], v94 offset:16320
	ds_read_b128 v[126:129], v94 offset:17344
	v_pk_fma_f32 v[28:29], v[114:115], v[34:35], v[36:37] op_sel_hi:[1,0,1] neg_lo:[0,1,0] neg_hi:[0,1,0]
	v_pk_fma_f32 v[30:31], v[116:117], v[34:35], v[38:39] op_sel_hi:[1,0,1] neg_lo:[0,1,0] neg_hi:[0,1,0]
	v_cndmask_b32_e64 v42, v42, v34, s[64:65]
	ds_read_b128 v[138:141], v94 offset:15216
	v_pk_mul_f32 v[24:25], v[30:31], v[136:137]
	v_pk_mul_f32 v[26:27], v[30:31], v[152:153]
	v_pk_fma_f32 v[24:25], v[28:29], v[134:135], v[24:25]
	v_pk_fma_f32 v[26:27], v[28:29], v[150:151], v[26:27]
	v_add_f32_e32 v34, v24, v25
	ds_read_b128 v[122:125], v94 offset:17088
	v_add_f32_e32 v61, v26, v27
	v_add_f32_dpp v34, v34, v34 quad_perm:[1,0,3,2] row_mask:0xf bank_mask:0xf bound_ctrl:1
	ds_read_b32 v130, v95 offset:17600
	ds_read_b128 v[118:121], v94 offset:16832
	v_add_f32_dpp v34, v34, v34 quad_perm:[2,3,0,1] row_mask:0xf bank_mask:0xf bound_ctrl:1
	s_waitcnt lgkmcnt(3)
	v_pk_mul_f32 v[36:37], v[146:147], v[154:155] op_sel_hi:[1,0]
	v_pk_mul_f32 v[38:39], v[148:149], v[154:155] op_sel_hi:[1,0]
	v_add_f32_dpp v34, v34, v34 row_ror:4 row_mask:0xf bank_mask:0xf bound_ctrl:1
	v_pk_fma_f32 v[36:37], v[28:29], v[142:143], v[36:37]
	v_pk_fma_f32 v[38:39], v[30:31], v[144:145], v[38:39]
	v_add_f32_dpp v34, v34, v34 row_ror:8 row_mask:0xf bank_mask:0xf bound_ctrl:1
	ds_read_b128 v[134:137], v94 offset:17680
	ds_read_b128 v[150:153], v94 offset:18704
	v_pk_fma_f32 v[28:29], v[138:139], v[34:35], v[36:37] op_sel_hi:[1,0,1] neg_lo:[0,1,0] neg_hi:[0,1,0]
	v_pk_fma_f32 v[30:31], v[140:141], v[34:35], v[38:39] op_sel_hi:[1,0,1] neg_lo:[0,1,0] neg_hi:[0,1,0]
	v_cndmask_b32_e64 v42, v42, v34, s[66:67]
	ds_read_b128 v[114:117], v94 offset:16576
	v_pk_mul_f32 v[24:25], v[30:31], v[112:113]
	v_pk_mul_f32 v[26:27], v[30:31], v[128:129]
	v_pk_fma_f32 v[24:25], v[28:29], v[110:111], v[24:25]
	v_pk_fma_f32 v[26:27], v[28:29], v[126:127], v[26:27]
	v_add_f32_e32 v34, v24, v25
	ds_read_b128 v[146:149], v94 offset:18448
	v_add_f32_e32 v62, v26, v27
	v_add_f32_dpp v34, v34, v34 quad_perm:[1,0,3,2] row_mask:0xf bank_mask:0xf bound_ctrl:1
	ds_read_b32 v154, v95 offset:18960
	ds_read_b128 v[142:145], v94 offset:18192
	v_add_f32_dpp v34, v34, v34 quad_perm:[2,3,0,1] row_mask:0xf bank_mask:0xf bound_ctrl:1
	s_waitcnt lgkmcnt(3)
	v_pk_mul_f32 v[36:37], v[122:123], v[130:131] op_sel_hi:[1,0]
	v_pk_mul_f32 v[38:39], v[124:125], v[130:131] op_sel_hi:[1,0]
	v_add_f32_dpp v34, v34, v34 row_ror:4 row_mask:0xf bank_mask:0xf bound_ctrl:1
	v_pk_fma_f32 v[36:37], v[28:29], v[118:119], v[36:37]
	v_pk_fma_f32 v[38:39], v[30:31], v[120:121], v[38:39]
	v_add_f32_dpp v34, v34, v34 row_ror:8 row_mask:0xf bank_mask:0xf bound_ctrl:1
	ds_read_b128 v[110:113], v94 offset:19040
	ds_read_b128 v[126:129], v94 offset:20064
	v_pk_fma_f32 v[28:29], v[114:115], v[34:35], v[36:37] op_sel_hi:[1,0,1] neg_lo:[0,1,0] neg_hi:[0,1,0]
	v_pk_fma_f32 v[30:31], v[116:117], v[34:35], v[38:39] op_sel_hi:[1,0,1] neg_lo:[0,1,0] neg_hi:[0,1,0]
	v_cndmask_b32_e64 v42, v42, v34, s[68:69]
	ds_read_b128 v[138:141], v94 offset:17936
	v_pk_mul_f32 v[24:25], v[30:31], v[136:137]
	v_pk_mul_f32 v[26:27], v[30:31], v[152:153]
	v_pk_fma_f32 v[24:25], v[28:29], v[134:135], v[24:25]
	v_pk_fma_f32 v[26:27], v[28:29], v[150:151], v[26:27]
	v_add_f32_e32 v34, v24, v25
	ds_read_b128 v[122:125], v94 offset:19808
	v_add_f32_e32 v63, v26, v27
	v_add_f32_dpp v34, v34, v34 quad_perm:[1,0,3,2] row_mask:0xf bank_mask:0xf bound_ctrl:1
	ds_read_b32 v130, v95 offset:20320
	ds_read_b128 v[118:121], v94 offset:19552
	v_add_f32_dpp v34, v34, v34 quad_perm:[2,3,0,1] row_mask:0xf bank_mask:0xf bound_ctrl:1
	s_waitcnt lgkmcnt(3)
	v_pk_mul_f32 v[36:37], v[146:147], v[154:155] op_sel_hi:[1,0]
	v_pk_mul_f32 v[38:39], v[148:149], v[154:155] op_sel_hi:[1,0]
	v_add_f32_dpp v34, v34, v34 row_ror:4 row_mask:0xf bank_mask:0xf bound_ctrl:1
	v_pk_fma_f32 v[36:37], v[28:29], v[142:143], v[36:37]
	v_pk_fma_f32 v[38:39], v[30:31], v[144:145], v[38:39]
	v_add_f32_dpp v34, v34, v34 row_ror:8 row_mask:0xf bank_mask:0xf bound_ctrl:1
	ds_read_b128 v[134:137], v94 offset:20400
	ds_read_b128 v[150:153], v94 offset:21424
	v_pk_fma_f32 v[28:29], v[138:139], v[34:35], v[36:37] op_sel_hi:[1,0,1] neg_lo:[0,1,0] neg_hi:[0,1,0]
	v_pk_fma_f32 v[30:31], v[140:141], v[34:35], v[38:39] op_sel_hi:[1,0,1] neg_lo:[0,1,0] neg_hi:[0,1,0]
	v_cndmask_b32_e64 v42, v42, v34, s[76:77]
	ds_read_b128 v[114:117], v94 offset:19296
	v_pk_mul_f32 v[24:25], v[30:31], v[112:113]
	v_pk_mul_f32 v[26:27], v[30:31], v[128:129]
	v_pk_fma_f32 v[24:25], v[28:29], v[110:111], v[24:25]
	v_pk_fma_f32 v[26:27], v[28:29], v[126:127], v[26:27]
	v_add_f32_e32 v34, v24, v25
	ds_read_b128 v[146:149], v94 offset:21168
	v_add_f32_e32 v64, v26, v27
	v_add_f32_dpp v34, v34, v34 quad_perm:[1,0,3,2] row_mask:0xf bank_mask:0xf bound_ctrl:1
	ds_read_b32 v154, v95 offset:21680
	ds_read_b128 v[142:145], v94 offset:20912
	v_add_f32_dpp v34, v34, v34 quad_perm:[2,3,0,1] row_mask:0xf bank_mask:0xf bound_ctrl:1
	s_waitcnt lgkmcnt(3)
	v_pk_mul_f32 v[36:37], v[122:123], v[130:131] op_sel_hi:[1,0]
	v_pk_mul_f32 v[38:39], v[124:125], v[130:131] op_sel_hi:[1,0]
	v_add_f32_dpp v34, v34, v34 row_ror:4 row_mask:0xf bank_mask:0xf bound_ctrl:1
	v_pk_fma_f32 v[36:37], v[28:29], v[118:119], v[36:37]
	v_pk_fma_f32 v[38:39], v[30:31], v[120:121], v[38:39]
	v_add_f32_dpp v34, v34, v34 row_ror:8 row_mask:0xf bank_mask:0xf bound_ctrl:1
	v_pk_fma_f32 v[28:29], v[114:115], v[34:35], v[36:37] op_sel_hi:[1,0,1] neg_lo:[0,1,0] neg_hi:[0,1,0]
	v_pk_fma_f32 v[30:31], v[116:117], v[34:35], v[38:39] op_sel_hi:[1,0,1] neg_lo:[0,1,0] neg_hi:[0,1,0]
	v_cndmask_b32_e32 v42, v42, v34, vcc
	ds_read_b128 v[138:141], v94 offset:20656
	v_pk_mul_f32 v[24:25], v[30:31], v[136:137]
	v_pk_mul_f32 v[26:27], v[30:31], v[152:153]
	v_pk_fma_f32 v[24:25], v[28:29], v[134:135], v[24:25]
	v_pk_fma_f32 v[26:27], v[28:29], v[150:151], v[26:27]
	v_add_f32_e32 v34, v24, v25
	v_lshl_add_u64 v[70:71], v[70:71], 0, s[2:3]
	v_add_f32_e32 v65, v26, v27
	v_add_f32_dpp v34, v34, v34 quad_perm:[1,0,3,2] row_mask:0xf bank_mask:0xf bound_ctrl:1
	v_lshl_add_u64 v[72:73], v[72:73], 0, s[20:21]
	v_lshl_add_u64 v[74:75], v[74:75], 0, s[20:21]
	v_add_f32_dpp v34, v34, v34 quad_perm:[2,3,0,1] row_mask:0xf bank_mask:0xf bound_ctrl:1
	s_waitcnt lgkmcnt(0)
	v_pk_mul_f32 v[36:37], v[146:147], v[154:155] op_sel_hi:[1,0]
	v_pk_mul_f32 v[38:39], v[148:149], v[154:155] op_sel_hi:[1,0]
	v_add_f32_dpp v34, v34, v34 row_ror:4 row_mask:0xf bank_mask:0xf bound_ctrl:1
	v_pk_fma_f32 v[36:37], v[28:29], v[142:143], v[36:37]
	v_pk_fma_f32 v[38:39], v[30:31], v[144:145], v[38:39]
	v_add_f32_dpp v34, v34, v34 row_ror:8 row_mask:0xf bank_mask:0xf bound_ctrl:1
	v_pk_fma_f32 v[28:29], v[138:139], v[34:35], v[36:37] op_sel_hi:[1,0,1] neg_lo:[0,1,0] neg_hi:[0,1,0]
	v_pk_fma_f32 v[30:31], v[140:141], v[34:35], v[38:39] op_sel_hi:[1,0,1] neg_lo:[0,1,0] neg_hi:[0,1,0]
	v_cndmask_b32_e64 v42, v42, v34, s[4:5]
	v_add_f32_dpp v50, v50, v50 row_ror:8 row_mask:0xf bank_mask:0xf bound_ctrl:1
	v_add_f32_dpp v51, v51, v51 row_ror:8 row_mask:0xf bank_mask:0xf bound_ctrl:1
	v_add_f32_dpp v52, v52, v52 row_ror:8 row_mask:0xf bank_mask:0xf bound_ctrl:1
	v_add_f32_dpp v53, v53, v53 row_ror:8 row_mask:0xf bank_mask:0xf bound_ctrl:1
	v_add_f32_dpp v54, v54, v54 row_ror:8 row_mask:0xf bank_mask:0xf bound_ctrl:1
	v_add_f32_dpp v55, v55, v55 row_ror:8 row_mask:0xf bank_mask:0xf bound_ctrl:1
	v_add_f32_dpp v56, v56, v56 row_ror:8 row_mask:0xf bank_mask:0xf bound_ctrl:1
	v_add_f32_dpp v57, v57, v57 row_ror:8 row_mask:0xf bank_mask:0xf bound_ctrl:1
	v_add_f32_dpp v50, v58, v58 row_ror:8 row_mask:0xf bank_mask:0xc bound_ctrl:1
	v_add_f32_dpp v51, v59, v59 row_ror:8 row_mask:0xf bank_mask:0xc bound_ctrl:1
	v_add_f32_dpp v52, v60, v60 row_ror:8 row_mask:0xf bank_mask:0xc bound_ctrl:1
	v_add_f32_dpp v53, v61, v61 row_ror:8 row_mask:0xf bank_mask:0xc bound_ctrl:1
	v_add_f32_dpp v54, v62, v62 row_ror:8 row_mask:0xf bank_mask:0xc bound_ctrl:1
	v_add_f32_dpp v55, v63, v63 row_ror:8 row_mask:0xf bank_mask:0xc bound_ctrl:1
	v_add_f32_dpp v56, v64, v64 row_ror:8 row_mask:0xf bank_mask:0xc bound_ctrl:1
	v_add_f32_dpp v57, v65, v65 row_ror:8 row_mask:0xf bank_mask:0xc bound_ctrl:1
	s_mov_b32 s2, 0xcccccccc
	s_mov_b32 s3, 0xcccccccc
	v_add_f32_dpp v50, v50, v50 row_half_mirror row_mask:0xf bank_mask:0x5 bound_ctrl:1
	v_add_f32_dpp v51, v51, v51 row_half_mirror row_mask:0xf bank_mask:0x5 bound_ctrl:1
	v_add_f32_dpp v52, v52, v52 row_half_mirror row_mask:0xf bank_mask:0x5 bound_ctrl:1
	v_add_f32_dpp v53, v53, v53 row_half_mirror row_mask:0xf bank_mask:0x5 bound_ctrl:1
	s_mov_b32 s20, 0xaaaaaaaa
	s_mov_b32 s21, 0xaaaaaaaa
	v_add_f32_dpp v50, v54, v54 row_half_mirror row_mask:0xf bank_mask:0xa bound_ctrl:1
	v_add_f32_dpp v51, v55, v55 row_half_mirror row_mask:0xf bank_mask:0xa bound_ctrl:1
	v_add_f32_dpp v52, v56, v56 row_half_mirror row_mask:0xf bank_mask:0xa bound_ctrl:1
	v_add_f32_dpp v53, v57, v57 row_half_mirror row_mask:0xf bank_mask:0xa bound_ctrl:1
	v_cndmask_b32_e64 v58, v52, v50, s[2:3]
	v_cndmask_b32_e64 v59, v53, v51, s[2:3]
	v_cndmask_b32_e64 v60, v50, v52, s[2:3]
	v_cndmask_b32_e64 v61, v51, v53, s[2:3]
	v_add_f32_dpp v50, v58, v60 quad_perm:[2,3,0,1] row_mask:0xf bank_mask:0xf bound_ctrl:1
	v_add_f32_dpp v51, v59, v61 quad_perm:[2,3,0,1] row_mask:0xf bank_mask:0xf bound_ctrl:1
	v_lshl_add_u64 v[24:25], v[68:69], 0, s[0:1]
	s_add_u32 s0, s0, 0x1000
	s_addc_u32 s1, s1, 0
	v_cndmask_b32_e64 v58, v51, v50, s[20:21]
	v_cndmask_b32_e64 v60, v50, v51, s[20:21]
	s_mov_b32 s24, s38
	s_cmp_lg_u32 s0, 0x54000
	v_add_f32_dpp v43, v58, v60 quad_perm:[1,0,3,2] row_mask:0xf bank_mask:0xf bound_ctrl:1
	v_fma_f32 v40, -v44, v42, v43
	v_fmac_f32_e32 v40, v48, v45
	global_store_dword v[24:25], v40, off
	s_barrier
	s_cbranch_scc0 .LBB0_233
